# B-loop vote: dead scalar load of blockDim removed (it raced with the s29 temp of the marker vote); otherwise identical to v79
# speedup vs baseline: 1.0041x; 1.0041x over previous
.LBB0_634:
	s_lshl_b32 s0, s3, 1
	s_or_b32 s24, s0, 1
	s_mul_i32 s0, s24, 0x2400
	s_add_i32 s26, s0, 0x100
	v_readlane_b32 s0, v252, 0
	v_add3_u32 v0, s26, v206, v207
	s_mulk_i32 s24, 0x3000
	v_readlane_b32 s1, v252, 1
	s_waitcnt vmcnt(1)
	ds_write_b128 v0, v[140:143]
	v_add_u32_e32 v0, s24, v208
	s_or_b64 s[0:1], s[16:17], s[60:61]
	s_waitcnt vmcnt(0)
	ds_write_b128 v0, v[136:139] offset:36864
	v_readlane_b32 s29, v250, 59
	s_add_i32 s50, s29, 4
	s_cmp_eq_u32 s50, 12
	s_cselect_b32 s50, 0, s50
	v_writelane_b32 v250, s50, 59
	v_mov_b32_e32 v0, s29
	v_add_u32_e32 v0, 32, v0
	v_mov_b32_e32 v2, s50
	v_add_u32_e32 v2, 32, v2
	v_cmp_eq_u32_e32 vcc, 0, v144
	s_and_saveexec_b64 s[50:51], vcc
	ds_write_b32 v2, v1
	s_mov_b64 exec, s[50:51]
	v_cmp_eq_u32_e32 vcc, 0, v199
	s_andn2_b64 vcc, vcc, s[0:1]
	s_and_saveexec_b64 s[50:51], vcc
	ds_write_b32 v0, v196
	s_mov_b64 exec, s[50:51]
	s_waitcnt lgkmcnt(0)
	s_barrier
	ds_read_b32 v0, v0
	s_waitcnt lgkmcnt(0)
	v_cmp_eq_u32_e32 vcc, 0, v0
	s_nop 1
	v_cndmask_b32_e64 v0, 0, 1, vcc
	s_branch .LBB0_620
